# FFN1 GEMM: LDS tile image re-laid out so every 1-KiB LDS-DMA piece reads 8 full 128-B rows (XOR-8 chunk swizzle) instead of 16 half rows
# baseline (speedup 1.0000x reference)
.LBB0_1906:
	s_andn2_b64 vcc, exec, s[0:1]
	s_cbranch_vccnz .LBB0_1977
	v_readlane_b32 s0, v254, 2
	v_readlane_b32 s1, v254, 3
	v_mbcnt_lo_u32_b32 v138, -1, 0
	v_mbcnt_hi_u32_b32 v138, -1, v138
	s_load_dwordx2 s[28:29], s[0:1], 0x100
	v_readlane_b32 s0, v254, 5
	s_waitcnt vmcnt(0)
	v_mbcnt_lo_u32_b32 v7, -1, 0
	v_mbcnt_hi_u32_b32 v7, -1, v7
	s_nop 0
	v_add_u32_e32 v0, s0, v7
	v_readlane_b32 s0, v254, 29
	v_readlane_b32 s1, v254, 30
	s_andn2_b64 vcc, exec, s[0:1]
	v_readfirstlane_b32 s0, v0
	s_cbranch_vccnz .LBB0_1923
	v_bfe_i32 v2, v0, 27, 1
	v_lshlrev_b32_e32 v1, 4, v0
	v_lshrrev_b32_e32 v2, 22, v2
	v_add_u32_e32 v2, v1, v2
	v_and_b32_e32 v2, 0xfffffc00, v2
	v_sub_u32_e32 v1, v1, v2
	v_lshrrev_b32_e32 v2, 4, v1
	v_ashrrev_i32_e32 v3, 31, v0
	v_bitop3_b32 v1, v2, v1, 32 bitop3:0x6c
	v_lshrrev_b32_e32 v3, 26, v3
	v_readlane_b32 s1, v255, 25
	s_waitcnt lgkmcnt(0)
	s_add_u32 s12, s28, 0x5000000
	v_ashrrev_i32_e32 v2, 31, v1
	v_add_u32_e32 v0, v0, v3
	s_mul_i32 s1, s1, 0xb00000
	s_addc_u32 s13, s29, 0
	v_lshrrev_b32_e32 v2, 26, v2
	v_ashrrev_i32_e32 v5, 6, v0
	s_add_u32 s1, s28, s1
	v_add_u32_e32 v2, v1, v2
	v_lshlrev_b32_e32 v0, 3, v5
	s_addc_u32 s2, s29, 0
	v_ashrrev_i32_e32 v4, 6, v2
	v_and_b32_e32 v0, -16, v0
	s_add_u32 s26, s1, 0x2b00000
	v_add_u32_e32 v0, v4, v0
	s_addc_u32 s27, s2, 0
	s_ashr_i32 s6, s0, 6
	v_and_b32_e32 v3, 3, v4
	s_mov_b32 s2, 0x1fffe0
	v_lshlrev_b32_e32 v6, 1, v0
	v_lshrrev_b32_e32 v8, 2, v0
	v_and_b32_e32 v2, 0xc0, v2
	s_ashr_i32 s1, s0, 8
	s_lshl_b32 s50, s6, 10
	v_and_or_b32 v3, v0, s2, v3
	v_and_b32_e32 v6, 24, v6
	v_and_b32_e32 v8, 4, v8
	v_sub_u32_e32 v1, v1, v2
	v_readlane_b32 s2, v254, 36
	v_or3_b32 v3, v3, v6, v8
	v_lshlrev_b32_e32 v6, 5, v5
	v_ashrrev_i16_sdwa v1, v231, sext(v1) dst_sel:DWORD dst_unused:UNUSED_PAD src0_sel:DWORD src1_sel:BYTE_0
	v_readlane_b32 s3, v254, 37
	s_add_u32 s54, s12, s2
	v_and_b32_e32 v8, 32, v6
	v_bfe_i32 v6, v1, 0, 16
	s_addc_u32 s55, s13, s3
	v_readlane_b32 s2, v254, 38
	v_add_lshl_u32 v1, v8, v6, 1
	v_readlane_b32 s3, v254, 39
	s_add_u32 s2, s26, s2
	v_lshl_add_u32 v184, v3, 11, v1
	s_addc_u32 s3, s27, s3
	s_add_i32 s51, s50, 0
	v_lshl_add_u32 v128, v0, 11, v1
	v_mbcnt_lo_u32_b32 v240, -1, 0
	v_mbcnt_hi_u32_b32 v240, -1, v240
	v_lshrrev_b32_e32 v241, 3, v240
	v_and_b32_e32 v242, 7, v240
	v_xor_b32_e32 v242, v242, v241
	v_lshlrev_b32_e32 v242, 4, v242
	v_lshl_add_u32 v243, s6, 3, v241
	v_lshl_add_u32 v128, v243, 11, v242
	v_and_b32_e32 v244, 32, v243
	v_bfe_u32 v241, v243, 2, 2
	v_lshl_add_u32 v244, v241, 3, v244
	v_bfe_u32 v241, v243, 4, 1
	v_lshl_add_u32 v244, v241, 2, v244
	v_and_b32_e32 v241, 3, v243
	v_add_u32_e32 v244, v244, v241
	v_lshl_add_u32 v184, v244, 11, v242
	v_lshl_add_u64 v[0:1], s[2:3], 0, v[184:185]
	s_add_i32 m0, s51, 0x10000
	v_lshl_add_u64 v[2:3], v[0:1], 0, s[84:85]
	global_load_lds_dwordx4 v184, s[2:3]
	s_add_i32 m0, s51, 0x12000
	v_mov_b32_e32 v129, v185
	global_load_lds_dwordx4 v[2:3], off
	v_lshl_add_u64 v[2:3], v[0:1], 0, s[86:87]
	s_add_i32 m0, s51, 0x14000
	s_add_i32 s66, s51, 0x2000
	global_load_lds_dwordx4 v[2:3], off
	v_lshl_add_u64 v[2:3], v[0:1], 0, s[88:89]
	s_add_i32 m0, s51, 0x16000
	s_add_i32 s67, s51, 0x4000
	global_load_lds_dwordx4 v[2:3], off
	v_lshl_add_u64 v[2:3], s[54:55], 0, v[128:129]
	s_mov_b32 m0, s51
	v_lshl_add_u64 v[8:9], v[2:3], 0, s[84:85]
	global_load_lds_dwordx4 v128, s[54:55]
	s_mov_b32 m0, s66
	s_add_i32 s76, s51, 0x6000
	global_load_lds_dwordx4 v[8:9], off
	v_lshl_add_u64 v[8:9], v[2:3], 0, s[86:87]
	s_mov_b32 m0, s67
	s_cmp_eq_u32 s1, 1
	global_load_lds_dwordx4 v[8:9], off
	v_lshl_add_u64 v[8:9], v[2:3], 0, s[88:89]
	s_mov_b32 m0, s76
	s_cselect_b64 s[8:9], -1, 0
	global_load_lds_dwordx4 v[8:9], off
	s_cmp_lg_u32 s1, 1
	s_cbranch_scc1 .LBB0_1910
	s_barrier
.LBB0_1910:
	v_readlane_b32 s10, v255, 26
	v_readlane_b32 s11, v255, 27
	s_mov_b32 s17, s11
	v_readlane_b32 s7, v255, 25
	s_mul_i32 s16, s7, 0x18000
	s_add_u32 s10, s28, 0xd000000
	s_mov_b32 s7, s17
	s_addc_u32 s11, s29, 0
	v_writelane_b32 v255, s6, 26
	s_lshl_b64 s[16:17], s[16:17], 2
	v_bfe_u32 v9, v7, 4, 2
	v_writelane_b32 v255, s7, 27
	s_add_u32 s7, s28, s16
	s_addc_u32 s17, s29, s17
	s_add_u32 s16, s7, 0x240000
	v_and_b32_e32 v8, 15, v7
	v_lshlrev_b32_e32 v10, 3, v9
	v_lshlrev_b32_e32 v9, 4, v9
	v_lshlrev_b32_e32 v7, 2, v7
	s_addc_u32 s17, s17, 0
	s_and_b32 s6, s6, 3
	v_lshl_or_b32 v139, s1, 6, v8
	v_lshl_or_b32 v8, v8, 6, v9
	s_lshl_b32 s1, s1, 13
	v_and_b32_e32 v7, 32, v7
	v_bitop3_b32 v11, v8, s1, v7 bitop3:0xde
	s_lshl_b32 s1, s6, 12
	v_bitop3_b32 v140, v8, s1, v7 bitop3:0xde
	v_lshl_add_u64 v[8:9], v[0:1], 0, s[90:91]
	s_add_i32 m0, s51, 0x18000
	s_waitcnt vmcnt(2)
	s_barrier
	global_load_lds_dwordx4 v[8:9], off
	v_lshl_add_u64 v[8:9], v[0:1], 0, s[92:93]
	s_add_i32 m0, s51, 0x1a000
	s_add_i32 s77, s51, 0x8000
	global_load_lds_dwordx4 v[8:9], off
	v_lshl_add_u64 v[8:9], v[2:3], 0, s[90:91]
	s_mov_b32 m0, s77
	s_add_i32 s78, s51, 0xa000
	global_load_lds_dwordx4 v[8:9], off
	v_lshl_add_u64 v[2:3], v[2:3], 0, s[92:93]
	s_mov_b32 m0, s78
	v_lshl_or_b32 v141, s6, 5, v10
	global_load_lds_dwordx4 v[2:3], off
	v_lshl_add_u64 v[2:3], v[0:1], 0, s[94:95]
	s_add_i32 m0, s51, 0x1c000
	v_lshl_add_u64 v[0:1], v[0:1], 0, s[96:97]
	global_load_lds_dwordx4 v[2:3], off
	s_add_i32 m0, s51, 0x1e000
	s_cmpk_lt_u32 s0, 0x100
	global_load_lds_dwordx4 v[0:1], off
	v_lshlrev_b32_e32 v0, 14, v5
	v_and_b32_e32 v0, 0xffff8000, v0
	s_waitcnt vmcnt(6)
	v_lshl_add_u32 v0, v4, 11, v0
	v_and_b32_e32 v1, 1, v5
	v_lshl_or_b32 v0, v1, 6, v0
	v_readlane_b32 s0, v254, 34
	s_cselect_b64 s[18:19], -1, 0
	v_lshl_add_u32 v130, v6, 1, v0
	v_mov_b32_e32 v130, v128
	v_mov_b32_e32 v131, v185
	s_mov_b32 s79, 0
	v_add_u32_e32 v142, 0, v11
	v_mbcnt_lo_u32_b32 v240, -1, 0
	v_mbcnt_hi_u32_b32 v240, -1, v240
	v_and_b32_e32 v241, 15, v240
	v_lshrrev_b32_e32 v242, 4, v240
	v_and_b32_e32 v243, 3, v241
	v_xor_b32_e32 v243, v243, v242
	v_lshlrev_b32_e32 v243, 4, v243
	v_bfe_u32 v244, v241, 2, 1
	v_lshl_or_b32 v243, v244, 6, v243
	v_and_b32_e32 v244, 7, v241
	v_lshl_or_b32 v243, v244, 7, v243
	v_bfe_u32 v244, v241, 3, 1
	v_lshl_or_b32 v243, v244, 10, v243
	v_and_b32_e32 v142, 0xffffe000, v142
	v_or_b32_e32 v142, v142, v243
	v_and_b32_e32 v140, 0xfffff000, v140
	v_or_b32_e32 v140, v140, v243
	v_xor_b32_e32 v245, 64, v142
	v_add_u32_e32 v246, 0x10000, v140
	v_xor_b32_e32 v247, 64, v246
	v_readlane_b32 s33, v254, 33
	s_mov_b32 s48, s0
	s_barrier
	v_readlane_b32 s1, v254, 35
	s_branch .LBB0_1913

.LBB0_1916:
	s_add_u32 s2, s54, 0xfffc0080
	s_addc_u32 s3, s55, -1
	s_add_i32 vcc_lo, 0, 0x10000
	s_cmp_eq_u32 s81, 12
	s_cselect_b32 s3, s0, s3
	s_cselect_b32 s2, s1, s2
	v_add_u32_e32 v136, vcc_lo, v140
	s_cselect_b32 s83, s23, s80
	s_cselect_b32 s82, s25, s49
	s_add_i32 vcc_hi, 0, 0x14000
	ds_read_b128 v[132:135], v246
	ds_read_b128 v[144:147], v247
	ds_read_b128 v[148:151], v246 offset:2048
	ds_read_b128 v[152:155], v247 offset:2048
	v_add_u32_e32 v136, vcc_hi, v140
	ds_read_b128 v[156:159], v246 offset:16384
	ds_read_b128 v[160:163], v247 offset:16384
	ds_read_b128 v[164:167], v246 offset:18432
	ds_read_b128 v[168:171], v247 offset:18432
	v_lshl_add_u64 v[136:137], s[54:55], 0, v[130:131]
	s_add_i32 m0, s51, 0xc000
	ds_read_b128 v[172:175], v142
	ds_read_b128 v[176:179], v245 offset:0
	ds_read_b128 v[180:183], v142 offset:2048
	ds_read_b128 v[200:203], v245 offset:2048
	ds_read_b128 v[204:207], v142 offset:4096
	ds_read_b128 v[208:211], v245 offset:4096
	ds_read_b128 v[212:215], v142 offset:6144
	ds_read_b128 v[216:219], v245 offset:6144
	global_load_lds_dwordx4 v[136:137], off
	v_lshl_add_u64 v[136:137], v[136:137], 0, s[84:85]
	s_add_i32 m0, s51, 0xe000
	s_nop 0
	global_load_lds_dwordx4 v[136:137], off
	s_waitcnt vmcnt(8)
	s_waitcnt lgkmcnt(0)
	s_barrier
	s_waitcnt lgkmcnt(0)
	v_mfma_f32_16x16x32_bf16 v[124:127], v[132:135], v[172:175], v[124:127]
	v_mfma_f32_16x16x32_bf16 v[120:123], v[148:151], v[172:175], v[120:123]
	v_mfma_f32_16x16x32_bf16 v[108:111], v[132:135], v[180:183], v[108:111]
	v_mfma_f32_16x16x32_bf16 v[104:107], v[148:151], v[180:183], v[104:107]
	v_mfma_f32_16x16x32_bf16 v[92:95], v[132:135], v[204:207], v[92:95]
	v_mfma_f32_16x16x32_bf16 v[88:91], v[148:151], v[204:207], v[88:91]
	v_mfma_f32_16x16x32_bf16 v[76:79], v[132:135], v[212:215], v[76:79]
	v_mfma_f32_16x16x32_bf16 v[72:75], v[148:151], v[212:215], v[72:75]
	v_mfma_f32_16x16x32_bf16 v[124:127], v[144:147], v[176:179], v[124:127]
	v_mfma_f32_16x16x32_bf16 v[120:123], v[152:155], v[176:179], v[120:123]
	v_mfma_f32_16x16x32_bf16 v[108:111], v[144:147], v[200:203], v[108:111]
	v_mfma_f32_16x16x32_bf16 v[104:107], v[152:155], v[200:203], v[104:107]
	v_mfma_f32_16x16x32_bf16 v[92:95], v[144:147], v[208:211], v[92:95]
	v_mfma_f32_16x16x32_bf16 v[88:91], v[152:155], v[208:211], v[88:91]
	v_mfma_f32_16x16x32_bf16 v[76:79], v[144:147], v[216:219], v[76:79]
	v_mfma_f32_16x16x32_bf16 v[72:75], v[152:155], v[216:219], v[72:75]
	v_mfma_f32_16x16x32_bf16 v[116:119], v[156:159], v[172:175], v[116:119]
	v_mfma_f32_16x16x32_bf16 v[112:115], v[164:167], v[172:175], v[112:115]
	v_mfma_f32_16x16x32_bf16 v[100:103], v[156:159], v[180:183], v[100:103]
	v_mfma_f32_16x16x32_bf16 v[96:99], v[164:167], v[180:183], v[96:99]
	v_mfma_f32_16x16x32_bf16 v[84:87], v[156:159], v[204:207], v[84:87]
	v_mfma_f32_16x16x32_bf16 v[80:83], v[164:167], v[204:207], v[80:83]
	v_mfma_f32_16x16x32_bf16 v[68:71], v[156:159], v[212:215], v[68:71]
	v_mfma_f32_16x16x32_bf16 v[64:67], v[164:167], v[212:215], v[64:67]
	v_mfma_f32_16x16x32_bf16 v[116:119], v[160:163], v[176:179], v[116:119]
	v_mfma_f32_16x16x32_bf16 v[112:115], v[168:171], v[176:179], v[112:115]
	v_mfma_f32_16x16x32_bf16 v[100:103], v[160:163], v[200:203], v[100:103]
	v_mfma_f32_16x16x32_bf16 v[96:99], v[168:171], v[200:203], v[96:99]
	v_mfma_f32_16x16x32_bf16 v[84:87], v[160:163], v[208:211], v[84:87]
	v_mfma_f32_16x16x32_bf16 v[80:83], v[168:171], v[208:211], v[80:83]
	v_mfma_f32_16x16x32_bf16 v[68:71], v[160:163], v[216:219], v[68:71]
	v_mfma_f32_16x16x32_bf16 v[64:67], v[168:171], v[216:219], v[64:67]
	s_barrier
	v_lshl_add_u64 v[136:137], s[82:83], 0, v[184:185]
	s_add_i32 s82, vcc_lo, s50
	s_mov_b32 m0, s82
	ds_read_b128 v[172:175], v142 offset:16384
	ds_read_b128 v[176:179], v245 offset:16384
	ds_read_b128 v[180:183], v142 offset:18432
	ds_read_b128 v[200:203], v245 offset:18432
	ds_read_b128 v[204:207], v142 offset:20480
	ds_read_b128 v[208:211], v245 offset:20480
	ds_read_b128 v[212:215], v142 offset:22528
	ds_read_b128 v[216:219], v245 offset:22528
	global_load_lds_dwordx4 v[136:137], off
	v_lshl_add_u64 v[220:221], v[136:137], 0, s[84:85]
	s_add_i32 m0, s82, 0x2000
	s_add_i32 s82, vcc_hi, s50
	global_load_lds_dwordx4 v[220:221], off
	v_lshl_add_u64 v[220:221], v[136:137], 0, s[86:87]
	s_mov_b32 m0, s82
	s_nop 0
	global_load_lds_dwordx4 v[220:221], off
	v_lshl_add_u64 v[220:221], v[136:137], 0, s[88:89]
	s_add_i32 m0, s82, 0x2000
	s_nop 0
	global_load_lds_dwordx4 v[220:221], off
	v_lshl_add_u64 v[220:221], s[2:3], 0, v[128:129]
	s_mov_b32 m0, s51
	v_lshl_add_u64 v[222:223], v[220:221], 0, s[84:85]
	global_load_lds_dwordx4 v[220:221], off
	s_mov_b32 m0, s66
	s_nop 0
	global_load_lds_dwordx4 v[222:223], off
	s_waitcnt vmcnt(8)
	s_waitcnt lgkmcnt(0)
	s_barrier
	s_waitcnt lgkmcnt(0)
	v_mfma_f32_16x16x32_bf16 v[60:63], v[132:135], v[172:175], v[60:63]
	v_mfma_f32_16x16x32_bf16 v[56:59], v[148:151], v[172:175], v[56:59]
	v_mfma_f32_16x16x32_bf16 v[44:47], v[132:135], v[180:183], v[44:47]
	v_mfma_f32_16x16x32_bf16 v[40:43], v[148:151], v[180:183], v[40:43]
	v_mfma_f32_16x16x32_bf16 v[28:31], v[132:135], v[204:207], v[28:31]
	v_mfma_f32_16x16x32_bf16 v[24:27], v[148:151], v[204:207], v[24:27]
	v_mfma_f32_16x16x32_bf16 v[12:15], v[132:135], v[212:215], v[12:15]
	v_mfma_f32_16x16x32_bf16 v[8:11], v[148:151], v[212:215], v[8:11]
	v_mfma_f32_16x16x32_bf16 v[60:63], v[144:147], v[176:179], v[60:63]
	v_mfma_f32_16x16x32_bf16 v[56:59], v[152:155], v[176:179], v[56:59]
	v_mfma_f32_16x16x32_bf16 v[44:47], v[144:147], v[200:203], v[44:47]
	v_mfma_f32_16x16x32_bf16 v[40:43], v[152:155], v[200:203], v[40:43]
	v_mfma_f32_16x16x32_bf16 v[28:31], v[144:147], v[208:211], v[28:31]
	v_mfma_f32_16x16x32_bf16 v[24:27], v[152:155], v[208:211], v[24:27]
	v_mfma_f32_16x16x32_bf16 v[12:15], v[144:147], v[216:219], v[12:15]
	v_mfma_f32_16x16x32_bf16 v[8:11], v[152:155], v[216:219], v[8:11]
	v_mfma_f32_16x16x32_bf16 v[52:55], v[156:159], v[172:175], v[52:55]
	v_mfma_f32_16x16x32_bf16 v[48:51], v[164:167], v[172:175], v[48:51]
	v_mfma_f32_16x16x32_bf16 v[36:39], v[156:159], v[180:183], v[36:39]
	v_mfma_f32_16x16x32_bf16 v[32:35], v[164:167], v[180:183], v[32:35]
	v_mfma_f32_16x16x32_bf16 v[20:23], v[156:159], v[204:207], v[20:23]
	v_mfma_f32_16x16x32_bf16 v[16:19], v[164:167], v[204:207], v[16:19]
	v_mfma_f32_16x16x32_bf16 v[4:7], v[156:159], v[212:215], v[4:7]
	v_mfma_f32_16x16x32_bf16 v[0:3], v[164:167], v[212:215], v[0:3]
	v_mfma_f32_16x16x32_bf16 v[52:55], v[160:163], v[176:179], v[52:55]
	v_mfma_f32_16x16x32_bf16 v[48:51], v[168:171], v[176:179], v[48:51]
	v_mfma_f32_16x16x32_bf16 v[36:39], v[160:163], v[200:203], v[36:39]
	v_mfma_f32_16x16x32_bf16 v[32:35], v[168:171], v[200:203], v[32:35]
	v_mfma_f32_16x16x32_bf16 v[20:23], v[160:163], v[208:211], v[20:23]
	v_mfma_f32_16x16x32_bf16 v[16:19], v[168:171], v[208:211], v[16:19]
	v_mfma_f32_16x16x32_bf16 v[4:7], v[160:163], v[216:219], v[4:7]
	v_mfma_f32_16x16x32_bf16 v[0:3], v[168:171], v[216:219], v[0:3]
	s_barrier
	s_add_i32 s2, 0, 0x18000
	v_add_u32_e32 v143, s2, v140
	s_add_i32 s3, 0, 0x1c000
	ds_read_b128 v[132:135], v246 offset:32768
	ds_read_b128 v[144:147], v247 offset:32768
	ds_read_b128 v[148:151], v246 offset:34816
	ds_read_b128 v[152:155], v247 offset:34816
	v_add_u32_e32 v143, s3, v140
	ds_read_b128 v[156:159], v246 offset:49152
	ds_read_b128 v[160:163], v247 offset:49152
	ds_read_b128 v[164:167], v246 offset:51200
	ds_read_b128 v[168:171], v247 offset:51200
	s_mov_b32 m0, s67
	v_lshl_add_u64 v[222:223], v[220:221], 0, s[86:87]
	ds_read_b128 v[172:175], v142 offset:32768
	ds_read_b128 v[176:179], v245 offset:32768
	ds_read_b128 v[180:183], v142 offset:34816
	ds_read_b128 v[200:203], v245 offset:34816
	ds_read_b128 v[204:207], v142 offset:36864
	ds_read_b128 v[208:211], v245 offset:36864
	ds_read_b128 v[212:215], v142 offset:38912
	ds_read_b128 v[216:219], v245 offset:38912
	global_load_lds_dwordx4 v[222:223], off
	v_lshl_add_u64 v[222:223], v[220:221], 0, s[88:89]
	s_mov_b32 m0, s76
	s_nop 0
	global_load_lds_dwordx4 v[222:223], off
	s_waitcnt vmcnt(8)
	s_waitcnt lgkmcnt(0)
	s_barrier
	s_waitcnt lgkmcnt(0)
	v_mfma_f32_16x16x32_bf16 v[124:127], v[132:135], v[172:175], v[124:127]
	v_mfma_f32_16x16x32_bf16 v[120:123], v[148:151], v[172:175], v[120:123]
	v_mfma_f32_16x16x32_bf16 v[108:111], v[132:135], v[180:183], v[108:111]
	v_mfma_f32_16x16x32_bf16 v[104:107], v[148:151], v[180:183], v[104:107]
	v_mfma_f32_16x16x32_bf16 v[92:95], v[132:135], v[204:207], v[92:95]
	v_mfma_f32_16x16x32_bf16 v[88:91], v[148:151], v[204:207], v[88:91]
	v_mfma_f32_16x16x32_bf16 v[76:79], v[132:135], v[212:215], v[76:79]
	v_mfma_f32_16x16x32_bf16 v[72:75], v[148:151], v[212:215], v[72:75]
	v_mfma_f32_16x16x32_bf16 v[124:127], v[144:147], v[176:179], v[124:127]
	v_mfma_f32_16x16x32_bf16 v[120:123], v[152:155], v[176:179], v[120:123]
	v_mfma_f32_16x16x32_bf16 v[108:111], v[144:147], v[200:203], v[108:111]
	v_mfma_f32_16x16x32_bf16 v[104:107], v[152:155], v[200:203], v[104:107]
	v_mfma_f32_16x16x32_bf16 v[92:95], v[144:147], v[208:211], v[92:95]
	v_mfma_f32_16x16x32_bf16 v[88:91], v[152:155], v[208:211], v[88:91]
	v_mfma_f32_16x16x32_bf16 v[76:79], v[144:147], v[216:219], v[76:79]
	v_mfma_f32_16x16x32_bf16 v[72:75], v[152:155], v[216:219], v[72:75]
	v_mfma_f32_16x16x32_bf16 v[116:119], v[156:159], v[172:175], v[116:119]
	v_mfma_f32_16x16x32_bf16 v[112:115], v[164:167], v[172:175], v[112:115]
	v_mfma_f32_16x16x32_bf16 v[100:103], v[156:159], v[180:183], v[100:103]
	v_mfma_f32_16x16x32_bf16 v[96:99], v[164:167], v[180:183], v[96:99]
	v_mfma_f32_16x16x32_bf16 v[84:87], v[156:159], v[204:207], v[84:87]
	v_mfma_f32_16x16x32_bf16 v[80:83], v[164:167], v[204:207], v[80:83]
	v_mfma_f32_16x16x32_bf16 v[68:71], v[156:159], v[212:215], v[68:71]
	v_mfma_f32_16x16x32_bf16 v[64:67], v[164:167], v[212:215], v[64:67]
	v_mfma_f32_16x16x32_bf16 v[116:119], v[160:163], v[176:179], v[116:119]
	v_mfma_f32_16x16x32_bf16 v[112:115], v[168:171], v[176:179], v[112:115]
	v_mfma_f32_16x16x32_bf16 v[100:103], v[160:163], v[200:203], v[100:103]
	v_mfma_f32_16x16x32_bf16 v[96:99], v[168:171], v[200:203], v[96:99]
	v_mfma_f32_16x16x32_bf16 v[84:87], v[160:163], v[208:211], v[84:87]
	v_mfma_f32_16x16x32_bf16 v[80:83], v[168:171], v[208:211], v[80:83]
	v_mfma_f32_16x16x32_bf16 v[68:71], v[160:163], v[216:219], v[68:71]
	v_mfma_f32_16x16x32_bf16 v[64:67], v[168:171], v[216:219], v[64:67]
	s_barrier
	s_add_i32 s2, s2, s50
	v_lshl_add_u64 v[222:223], v[136:137], 0, s[90:91]
	s_mov_b32 m0, s2
	ds_read_b128 v[172:175], v142 offset:49152
	ds_read_b128 v[176:179], v245 offset:49152
	ds_read_b128 v[180:183], v142 offset:51200
	ds_read_b128 v[200:203], v245 offset:51200
	ds_read_b128 v[204:207], v142 offset:53248
	ds_read_b128 v[208:211], v245 offset:53248
	ds_read_b128 v[212:215], v142 offset:55296
	ds_read_b128 v[216:219], v245 offset:55296
	global_load_lds_dwordx4 v[222:223], off
	v_lshl_add_u64 v[222:223], v[136:137], 0, s[92:93]
	s_add_i32 m0, s2, 0x2000
	s_add_i32 s2, s3, s50
	global_load_lds_dwordx4 v[222:223], off
	v_lshl_add_u64 v[222:223], v[136:137], 0, s[94:95]
	s_mov_b32 m0, s2
	v_lshl_add_u64 v[136:137], v[136:137], 0, s[96:97]
	global_load_lds_dwordx4 v[222:223], off
	s_add_i32 m0, s2, 0x2000
	s_nop 0
	global_load_lds_dwordx4 v[136:137], off
	v_lshl_add_u64 v[136:137], v[220:221], 0, s[90:91]
	s_mov_b32 m0, s77
	s_nop 0
	global_load_lds_dwordx4 v[136:137], off
	v_lshl_add_u64 v[136:137], v[220:221], 0, s[92:93]
	s_mov_b32 m0, s78
	s_nop 0
	global_load_lds_dwordx4 v[136:137], off
	s_waitcnt vmcnt(8)
	s_waitcnt lgkmcnt(0)
	s_barrier
	s_waitcnt lgkmcnt(0)
	v_mfma_f32_16x16x32_bf16 v[60:63], v[132:135], v[172:175], v[60:63]
	v_mfma_f32_16x16x32_bf16 v[56:59], v[148:151], v[172:175], v[56:59]
	v_mfma_f32_16x16x32_bf16 v[44:47], v[132:135], v[180:183], v[44:47]
	v_mfma_f32_16x16x32_bf16 v[40:43], v[148:151], v[180:183], v[40:43]
	v_mfma_f32_16x16x32_bf16 v[28:31], v[132:135], v[204:207], v[28:31]
	v_mfma_f32_16x16x32_bf16 v[24:27], v[148:151], v[204:207], v[24:27]
	v_mfma_f32_16x16x32_bf16 v[12:15], v[132:135], v[212:215], v[12:15]
	v_mfma_f32_16x16x32_bf16 v[8:11], v[148:151], v[212:215], v[8:11]
	v_mfma_f32_16x16x32_bf16 v[60:63], v[144:147], v[176:179], v[60:63]
	v_mfma_f32_16x16x32_bf16 v[56:59], v[152:155], v[176:179], v[56:59]
	v_mfma_f32_16x16x32_bf16 v[44:47], v[144:147], v[200:203], v[44:47]
	v_mfma_f32_16x16x32_bf16 v[40:43], v[152:155], v[200:203], v[40:43]
	v_mfma_f32_16x16x32_bf16 v[28:31], v[144:147], v[208:211], v[28:31]
	v_mfma_f32_16x16x32_bf16 v[24:27], v[152:155], v[208:211], v[24:27]
	v_mfma_f32_16x16x32_bf16 v[12:15], v[144:147], v[216:219], v[12:15]
	v_mfma_f32_16x16x32_bf16 v[8:11], v[152:155], v[216:219], v[8:11]
	v_mfma_f32_16x16x32_bf16 v[52:55], v[156:159], v[172:175], v[52:55]
	v_mfma_f32_16x16x32_bf16 v[48:51], v[164:167], v[172:175], v[48:51]
	v_mfma_f32_16x16x32_bf16 v[36:39], v[156:159], v[180:183], v[36:39]
	v_mfma_f32_16x16x32_bf16 v[32:35], v[164:167], v[180:183], v[32:35]
	v_mfma_f32_16x16x32_bf16 v[20:23], v[156:159], v[204:207], v[20:23]
	v_mfma_f32_16x16x32_bf16 v[16:19], v[164:167], v[204:207], v[16:19]
	v_mfma_f32_16x16x32_bf16 v[4:7], v[156:159], v[212:215], v[4:7]
	v_mfma_f32_16x16x32_bf16 v[0:3], v[164:167], v[212:215], v[0:3]
	v_mfma_f32_16x16x32_bf16 v[52:55], v[160:163], v[176:179], v[52:55]
	v_mfma_f32_16x16x32_bf16 v[48:51], v[168:171], v[176:179], v[48:51]
	v_mfma_f32_16x16x32_bf16 v[36:39], v[160:163], v[200:203], v[36:39]
	v_mfma_f32_16x16x32_bf16 v[32:35], v[168:171], v[200:203], v[32:35]
	v_mfma_f32_16x16x32_bf16 v[20:23], v[160:163], v[208:211], v[20:23]
	v_mfma_f32_16x16x32_bf16 v[16:19], v[168:171], v[208:211], v[16:19]
	v_mfma_f32_16x16x32_bf16 v[4:7], v[160:163], v[216:219], v[4:7]
	v_mfma_f32_16x16x32_bf16 v[0:3], v[168:171], v[216:219], v[0:3]
	s_barrier
	s_add_i32 s81, s81, 2
	s_add_u32 s54, s54, 0x100
	s_addc_u32 s55, s55, 0
	s_add_u32 s49, s49, 0x100
	s_addc_u32 s80, s80, 0
	s_cmp_gt_u32 s81, 13
	s_cbranch_scc0 .LBB0_1916
	s_and_b64 vcc, exec, s[18:19]
	s_cbranch_vccz .LBB0_1919
	s_barrier
